# NSA selected branch fast path: early mask-probe prefetch combined with the compute-segment priority raise
# speedup vs baseline: 1.0146x; 1.0101x over previous
; DI void nsa_item(const Params& p, int bk, int qb, char* smem, float Mb) {
;     ...
;                 for (int k4 = 0; k4 < 4; ++k4) {
;                     kf[k4][0] = *(const bf16x8*)(kb_ + k4 * 16 * 144); kf[k4][1] = *(const bf16x8*)(kb_ + k4 * 16 * 144 + 64);
;                     vf[k4][0] = *(const bf16x8*)(kb_ + 9216 + k4 * 16 * 144); vf[k4][1] = *(const bf16x8*)(kb_ + 9216 + k4 * 16 * 144 + 64);
;                 }
;                 const bool mine = (sub >> fr) & 1u;
;                 const float Ml = mine ? Mb : 3.0e38f;
;                 const bool diag = (j == cur);
; #pragma unroll
;                 for (int g = 0; g < 3; ++g) {
;                     f32x4 st[4];
;                     st_from(kf, qf[g], st, -Ml);
;                     if (diag) {
; #pragma unroll
;                         for (int k4 = 0; k4 < 4; ++k4)
; #pragma unroll
;                             for (int ii = 0; ii < 4; ++ii) {
;                                 const float pv = (j * 64 + k4 * 16 + fq * 4 + ii <= tq) ? __builtin_amdgcn_exp2f(st[k4][ii]) : 0.f;
;                                 st[k4][ii] = pv; ls[g] += pv;
;                             }
;                     } else {
; #pragma unroll
;                         for (int k4 = 0; k4 < 4; ++k4)
; #pragma unroll
;                             for (int ii = 0; ii < 4; ++ii) { const float pv = __builtin_amdgcn_exp2f(st[k4][ii]); st[k4][ii] = pv; ls[g] += pv; }
;                     }
;                     pv_from(vf, st, o[g]);
.Lsel_fast:
	s_setprio 1
	ds_read_b128 v[140:143], v116 offset:6976
	ds_read_b128 v[108:111], v116 offset:9216
	ds_read_b128 v[88:91], v116 offset:9280
	ds_read_b128 v[92:95], v116 offset:11520
	ds_read_b128 v[96:99], v116 offset:11584
	ds_read_b128 v[100:103], v116 offset:13824
	ds_read_b128 v[104:107], v116 offset:13888
	ds_read_b128 v[112:115], v116 offset:16128
	s_waitcnt lgkmcnt(7)
	ds_read_b128 v[116:119], v116 offset:16192
	v_mfma_f32_16x16x32_bf16 v[156:159], v[120:123], v[0:3], v[124:127]
	v_mfma_f32_16x16x32_bf16 v[164:167], v[132:135], v[0:3], v[124:127]
	v_mfma_f32_16x16x32_bf16 v[172:175], v[144:147], v[0:3], v[124:127]
	v_mfma_f32_16x16x32_bf16 v[180:183], v[152:155], v[0:3], v[124:127]
	v_mfma_f32_16x16x32_bf16 v[156:159], v[128:131], v[4:7], v[156:159]
	v_mfma_f32_16x16x32_bf16 v[164:167], v[136:139], v[4:7], v[164:167]
	v_mfma_f32_16x16x32_bf16 v[172:175], v[148:151], v[4:7], v[172:175]
	v_mfma_f32_16x16x32_bf16 v[180:183], v[140:143], v[4:7], v[180:183]
	v_mfma_f32_16x16x32_bf16 v[184:187], v[120:123], v[8:11], v[124:127]
	v_mfma_f32_16x16x32_bf16 v[176:179], v[132:135], v[8:11], v[124:127]
	v_mfma_f32_16x16x32_bf16 v[168:171], v[144:147], v[8:11], v[124:127]
	v_mfma_f32_16x16x32_bf16 v[160:163], v[152:155], v[8:11], v[124:127]
	s_nop 1
	v_mfma_f32_16x16x32_bf16 v[184:187], v[128:131], v[12:15], v[184:187]
	v_exp_f32_e32 v156, v156
	v_exp_f32_e32 v157, v157
	v_exp_f32_e32 v158, v158
	v_exp_f32_e32 v159, v159
	v_mfma_f32_16x16x32_bf16 v[176:179], v[136:139], v[12:15], v[176:179]
	v_exp_f32_e32 v164, v164
	v_exp_f32_e32 v165, v165
	v_exp_f32_e32 v166, v166
	v_exp_f32_e32 v167, v167
	v_mfma_f32_16x16x32_bf16 v[168:171], v[148:151], v[12:15], v[168:171]
	v_exp_f32_e32 v172, v172
	v_exp_f32_e32 v173, v173
	v_exp_f32_e32 v174, v174
	v_exp_f32_e32 v175, v175
	v_mfma_f32_16x16x32_bf16 v[160:163], v[140:143], v[12:15], v[160:163]
	v_exp_f32_e32 v180, v180
	v_exp_f32_e32 v181, v181
	v_exp_f32_e32 v182, v182
	v_exp_f32_e32 v183, v183
	v_pk_add_f32 v[254:255], v[156:157], v[158:159]
	v_pk_add_f32 v[254:255], v[254:255], v[164:165]
	v_pk_add_f32 v[254:255], v[254:255], v[166:167]
	v_cvt_pk_bf16_f32 v156, v156, v157
	v_cvt_pk_bf16_f32 v157, v158, v159
	v_cvt_pk_bf16_f32 v158, v164, v165
	v_cvt_pk_bf16_f32 v159, v166, v167
	v_pk_add_f32 v[164:165], v[172:173], v[174:175]
	v_pk_add_f32 v[164:165], v[164:165], v[180:181]
	v_pk_add_f32 v[164:165], v[164:165], v[182:183]
	v_cvt_pk_bf16_f32 v172, v172, v173
	v_cvt_pk_bf16_f32 v173, v174, v175
	v_cvt_pk_bf16_f32 v174, v180, v181
	v_cvt_pk_bf16_f32 v175, v182, v183
	v_pk_add_f32 v[254:255], v[254:255], v[164:165]
	v_add_f32_e32 v244, v244, v254
	v_add_f32_e32 v244, v244, v255
	s_waitcnt lgkmcnt(0)
; DI void nsa_item(const Params& p, int bk, int qb, char* smem, float Mb) {
;     ...
;                 const unsigned long long mm = masks[j];
;                 const unsigned mlo = __builtin_amdgcn_readfirstlane((unsigned)mm), mhi = __builtin_amdgcn_readfirstlane((unsigned)(mm >> 32));
;     ...
;                 for (int g = 0; g < 3; ++g) {
;                     f32x4 st[4];
;                     st_from(kf, qf[g], st, -Ml);
;                     if (diag) {
; #pragma unroll
;                         for (int k4 = 0; k4 < 4; ++k4)
; #pragma unroll
;                             for (int ii = 0; ii < 4; ++ii) {
;                                 const float pv = (j * 64 + k4 * 16 + fq * 4 + ii <= tq) ? __builtin_amdgcn_exp2f(st[k4][ii]) : 0.f;
;                                 st[k4][ii] = pv; ls[g] += pv;
;                             }
;                     } else {
; #pragma unroll
;                         for (int k4 = 0; k4 < 4; ++k4)
; #pragma unroll
;                             for (int ii = 0; ii < 4; ++ii) { const float pv = __builtin_amdgcn_exp2f(st[k4][ii]); st[k4][ii] = pv; ls[g] += pv; }
;                     }
;                     pv_from(vf, st, o[g]);
;                 }
;             }
;             lstore(bsel ^ 1);
;             __syncthreads();
;             bsel ^= 1; j = jn; m = mn;
	s_nop 1
	v_mfma_f32_16x16x32_bf16 v[68:71], v[108:111], v[156:159], v[68:71]
	v_exp_f32_e32 v184, v184
	v_mfma_f32_16x16x32_bf16 v[64:67], v[92:95], v[156:159], v[64:67]
	v_exp_f32_e32 v185, v185
	v_mfma_f32_16x16x32_bf16 v[60:63], v[100:103], v[156:159], v[60:63]
	v_exp_f32_e32 v186, v186
	v_mfma_f32_16x16x32_bf16 v[56:59], v[112:115], v[156:159], v[56:59]
	v_exp_f32_e32 v187, v187
	v_mfma_f32_16x16x32_bf16 v[68:71], v[88:91], v[172:175], v[68:71]
	v_exp_f32_e32 v176, v176
	v_mfma_f32_16x16x32_bf16 v[64:67], v[96:99], v[172:175], v[64:67]
	v_exp_f32_e32 v177, v177
	v_mfma_f32_16x16x32_bf16 v[60:63], v[104:107], v[172:175], v[60:63]
	v_exp_f32_e32 v178, v178
	v_mfma_f32_16x16x32_bf16 v[56:59], v[116:119], v[172:175], v[56:59]
	v_exp_f32_e32 v179, v179
	v_mfma_f32_16x16x32_bf16 v[156:159], v[120:123], v[16:19], v[124:127]
	v_exp_f32_e32 v168, v168
	v_mfma_f32_16x16x32_bf16 v[164:167], v[132:135], v[16:19], v[124:127]
	v_exp_f32_e32 v169, v169
	v_mfma_f32_16x16x32_bf16 v[172:175], v[144:147], v[16:19], v[124:127]
	v_exp_f32_e32 v170, v170
	v_mfma_f32_16x16x32_bf16 v[180:183], v[152:155], v[16:19], v[124:127]
	v_exp_f32_e32 v171, v171
	v_mfma_f32_16x16x32_bf16 v[156:159], v[128:131], v[20:23], v[156:159]
	v_exp_f32_e32 v160, v160
	v_mfma_f32_16x16x32_bf16 v[164:167], v[136:139], v[20:23], v[164:167]
	v_exp_f32_e32 v161, v161
	v_mfma_f32_16x16x32_bf16 v[172:175], v[148:151], v[20:23], v[172:175]
	v_exp_f32_e32 v162, v162
	v_mfma_f32_16x16x32_bf16 v[180:183], v[140:143], v[20:23], v[180:183]
	v_exp_f32_e32 v163, v163
	v_pk_add_f32 v[254:255], v[184:185], v[186:187]
	v_pk_add_f32 v[254:255], v[254:255], v[176:177]
	v_pk_add_f32 v[254:255], v[254:255], v[178:179]
	v_cvt_pk_bf16_f32 v184, v184, v185
	v_cvt_pk_bf16_f32 v185, v186, v187
	v_cvt_pk_bf16_f32 v186, v176, v177
	v_cvt_pk_bf16_f32 v187, v178, v179
	v_pk_add_f32 v[176:177], v[168:169], v[170:171]
	v_pk_add_f32 v[176:177], v[176:177], v[160:161]
	v_pk_add_f32 v[176:177], v[176:177], v[162:163]
	v_cvt_pk_bf16_f32 v168, v168, v169
	v_cvt_pk_bf16_f32 v169, v170, v171
	v_cvt_pk_bf16_f32 v170, v160, v161
	v_cvt_pk_bf16_f32 v171, v162, v163
	v_pk_add_f32 v[254:255], v[254:255], v[176:177]
	v_add_f32_e32 v243, v243, v254
	v_add_f32_e32 v243, v243, v255
	s_nop 1
	v_mfma_f32_16x16x32_bf16 v[52:55], v[108:111], v[184:187], v[52:55]
	v_exp_f32_e32 v156, v156
	v_exp_f32_e32 v157, v157
	v_mfma_f32_16x16x32_bf16 v[48:51], v[92:95], v[184:187], v[48:51]
	v_exp_f32_e32 v158, v158
	v_exp_f32_e32 v159, v159
	v_mfma_f32_16x16x32_bf16 v[44:47], v[100:103], v[184:187], v[44:47]
	v_exp_f32_e32 v164, v164
	v_exp_f32_e32 v165, v165
	v_mfma_f32_16x16x32_bf16 v[40:43], v[112:115], v[184:187], v[40:43]
	v_exp_f32_e32 v166, v166
	v_exp_f32_e32 v167, v167
	v_mfma_f32_16x16x32_bf16 v[52:55], v[88:91], v[168:171], v[52:55]
	v_exp_f32_e32 v172, v172
	v_exp_f32_e32 v173, v173
	v_mfma_f32_16x16x32_bf16 v[48:51], v[96:99], v[168:171], v[48:51]
	v_exp_f32_e32 v174, v174
	v_exp_f32_e32 v175, v175
	v_mfma_f32_16x16x32_bf16 v[44:47], v[104:107], v[168:171], v[44:47]
	v_exp_f32_e32 v180, v180
	v_exp_f32_e32 v181, v181
	v_mfma_f32_16x16x32_bf16 v[40:43], v[116:119], v[168:171], v[40:43]
	v_exp_f32_e32 v182, v182
	v_exp_f32_e32 v183, v183
	v_pk_add_f32 v[254:255], v[156:157], v[158:159]
	v_pk_add_f32 v[254:255], v[254:255], v[164:165]
	v_pk_add_f32 v[254:255], v[254:255], v[166:167]
	v_cvt_pk_bf16_f32 v156, v156, v157
	v_cvt_pk_bf16_f32 v157, v158, v159
	v_cvt_pk_bf16_f32 v158, v164, v165
	v_cvt_pk_bf16_f32 v159, v166, v167
	v_pk_add_f32 v[164:165], v[172:173], v[174:175]
	v_pk_add_f32 v[164:165], v[164:165], v[180:181]
	v_pk_add_f32 v[164:165], v[164:165], v[182:183]
	v_cvt_pk_bf16_f32 v172, v172, v173
	v_cvt_pk_bf16_f32 v173, v174, v175
	v_cvt_pk_bf16_f32 v174, v180, v181
	v_cvt_pk_bf16_f32 v175, v182, v183
	v_pk_add_f32 v[254:255], v[254:255], v[164:165]
	v_add_f32_e32 v241, v241, v254
	v_add_f32_e32 v241, v241, v255
	s_or_b64 exec, exec, s[12:13]
	s_and_b64 s[4:5], exec, s[4:5]
	s_or_b64 s[10:11], s[4:5], s[10:11]
	s_xor_b32 s22, s22, 1
	s_mul_i32 s4, s22, 0x4800
	v_add_u32_e32 v254, s4, v195
	v_readlane_b32 s2, v249, 29
	s_waitcnt vmcnt(3)
	ds_write_b128 v254, v[72:75]
	v_mfma_f32_16x16x32_bf16 v[36:39], v[108:111], v[156:159], v[36:39]
	v_mfma_f32_16x16x32_bf16 v[32:35], v[92:95], v[156:159], v[32:35]
	s_waitcnt vmcnt(2)
	ds_write_b128 v254, v[76:79] offset:4608
	v_lshl_add_u32 v72, v242, 3, s2
	ds_read_b64 v[72:73], v72
	v_mfma_f32_16x16x32_bf16 v[28:31], v[100:103], v[156:159], v[28:31]
	v_mfma_f32_16x16x32_bf16 v[24:27], v[112:115], v[156:159], v[24:27]
	s_waitcnt vmcnt(1)
	ds_write_b128 v254, v[80:83] offset:9216
	v_mfma_f32_16x16x32_bf16 v[36:39], v[88:91], v[172:175], v[36:39]
	v_mfma_f32_16x16x32_bf16 v[32:35], v[96:99], v[172:175], v[32:35]
	s_waitcnt vmcnt(0)
	ds_write_b128 v254, v[84:87] offset:13824
	v_mfma_f32_16x16x32_bf16 v[28:31], v[104:107], v[172:175], v[28:31]
	v_mfma_f32_16x16x32_bf16 v[24:27], v[116:119], v[172:175], v[24:27]
	s_setprio 0
	s_branch .Lsel_bot3
